# v62 + P4/P9 epilogue start: leftover compiler waits (vmcnt(0)/(1), lgkmcnt(0)) and nops after the rstd prelude removed, so the reuse path no longer drains the next unit's DMA prefetch
# speedup vs baseline: 1.0154x; 1.0078x over previous
.Lrstd_done_p4:
	v_or_b32_e32 v160, 16, v162
	v_or_b32_e32 v156, 32, v162
	v_or_b32_e32 v154, 48, v162
	v_add_u32_e32 v148, 0x80, v162
	v_add_u32_e32 v152, 0x90, v162
	v_add_u32_e32 v150, 0xa0, v162
	v_add_u32_e32 v146, 0xb0, v162
	v_mov_b32_e32 v180, v120
	v_mov_b32_e32 v181, v124
	v_pk_mul_f32 v[180:181], v[180:181], v[176:177] op_sel_hi:[1,0]
	v_mov_b32_e32 v124, v121
	v_mul_f32_e32 v120, 0xbfb8aa3b, v181
	v_exp_f32_e32 v147, v120
	v_pk_mul_f32 v[120:121], v[124:125], v[176:177] op_sel_hi:[1,0]
	s_andn2_b64 vcc, exec, s[6:7]
	v_mul_f32_e32 v124, 0xbfb8aa3b, v121
	v_exp_f32_e32 v125, v124
	v_add_f32_e32 v147, 1.0, v147
	v_rcp_f32_e32 v147, v147
	v_lshl_or_b32 v124, s33, 7, v167
	v_add_f32_e32 v125, 1.0, v125
	v_rcp_f32_e32 v149, v125
	v_mul_f32_e32 v147, v181, v147
	v_mul_f32_e32 v147, v180, v147
	v_mov_b32_e32 v180, v122
	v_mov_b32_e32 v181, v126
	v_pk_mul_f32 v[180:181], v[180:181], v[176:177] op_sel_hi:[1,0]
	v_mov_b32_e32 v126, v123
	v_mul_f32_e32 v122, 0xbfb8aa3b, v181
	v_mul_f32_e32 v121, v121, v149
	v_exp_f32_e32 v149, v122
	v_pk_mul_f32 v[122:123], v[126:127], v[176:177] op_sel_hi:[1,0]
	v_mul_f32_e32 v127, v120, v121
	v_mul_f32_e32 v126, 0xbfb8aa3b, v123
	v_exp_f32_e32 v126, v126
	v_add_f32_e32 v120, 1.0, v149
	v_rcp_f32_e32 v149, v120
	v_mov_b32_e32 v121, v116
	v_add_f32_e32 v120, 1.0, v126
	v_rcp_f32_e32 v126, v120
	v_mov_b32_e32 v120, v112
	v_pk_mul_f32 v[120:121], v[120:121], v[176:177] op_sel_hi:[1,0]
	v_mul_f32_e32 v116, v181, v149
	v_mul_f32_e32 v112, 0xbfb8aa3b, v121
	v_exp_f32_e32 v112, v112
	v_mul_f32_e32 v149, v180, v116
	v_mov_b32_e32 v116, v113
	v_mul_f32_e32 v123, v123, v126
	v_add_f32_e32 v112, 1.0, v112
	v_rcp_f32_e32 v126, v112
	v_pk_mul_f32 v[112:113], v[116:117], v[176:177] op_sel_hi:[1,0]
	v_mul_f32_e32 v122, v122, v123
	v_mul_f32_e32 v116, 0xbfb8aa3b, v113
	v_exp_f32_e32 v116, v116
	v_mul_f32_e32 v117, v121, v126
	v_mul_f32_e32 v120, v120, v117
	v_mov_b32_e32 v117, v118
	v_add_f32_e32 v116, 1.0, v116
	v_rcp_f32_e32 v121, v116
	v_mov_b32_e32 v116, v114
	v_pk_mul_f32 v[116:117], v[116:117], v[176:177] op_sel_hi:[1,0]
	v_mov_b32_e32 v118, v115
	v_mul_f32_e32 v114, 0xbfb8aa3b, v117
	v_exp_f32_e32 v123, v114
	v_pk_mul_f32 v[114:115], v[118:119], v[176:177] op_sel_hi:[1,0]
	v_mul_f32_e32 v113, v113, v121
	v_mul_f32_e32 v118, 0xbfb8aa3b, v115
	v_exp_f32_e32 v118, v118
	v_add_f32_e32 v119, 1.0, v123
	v_rcp_f32_e32 v119, v119
	v_mul_f32_e32 v112, v112, v113
	v_add_f32_e32 v118, 1.0, v118
	v_rcp_f32_e32 v118, v118
	v_mul_f32_e32 v113, v117, v119
	v_mul_f32_e32 v113, v116, v113
	v_cvt_pk_bf16_f32 v116, v147, v127
	v_cvt_pk_bf16_f32 v117, v149, v122
	v_mov_b32_e32 v122, v104
	v_mov_b32_e32 v123, v108
	v_mul_f32_e32 v115, v115, v118
	v_pk_mul_f32 v[122:123], v[122:123], v[174:175] op_sel_hi:[1,0]
	v_ashrrev_i32_e32 v125, 31, v124
	v_mul_f32_e32 v114, v114, v115
	v_mul_f32_e32 v104, 0xbfb8aa3b, v123
	v_cvt_pk_bf16_f32 v118, v120, v112
	v_cvt_pk_bf16_f32 v119, v113, v114
	v_lshlrev_b64 v[114:115], 1, v[124:125]
	v_exp_f32_e32 v124, v104
	v_mov_b32_e32 v108, v105
	v_mov_b64_e32 v[112:113], s[26:27]
	v_pk_mul_f32 v[104:105], v[108:109], v[174:175] op_sel_hi:[1,0]
	v_mad_i64_i32 v[120:121], s[4:5], v162, s52, v[112:113]
	v_mul_f32_e32 v108, 0xbfb8aa3b, v105
	v_exp_f32_e32 v125, v108
	v_lshl_add_u64 v[108:109], v[120:121], 0, v[114:115]
	v_add_f32_e32 v120, 1.0, v124
	v_rcp_f32_e32 v120, v120
	global_store_dwordx4 v[108:109], v[116:119], off
	v_mov_b32_e32 v109, v110
	v_add_f32_e32 v121, 1.0, v125
	v_mul_f32_e32 v108, v123, v120
	v_mul_f32_e32 v116, v122, v108
	v_mov_b32_e32 v108, v106
	v_pk_mul_f32 v[108:109], v[108:109], v[174:175] op_sel_hi:[1,0]
	v_mov_b32_e32 v110, v107
	v_mul_f32_e32 v106, 0xbfb8aa3b, v109
	v_rcp_f32_e32 v121, v121
	v_exp_f32_e32 v117, v106
	v_pk_mul_f32 v[106:107], v[110:111], v[174:175] op_sel_hi:[1,0]
	v_mul_f32_e32 v105, v105, v121
	v_mul_f32_e32 v110, 0xbfb8aa3b, v107
	v_exp_f32_e32 v110, v110
	v_mul_f32_e32 v111, v104, v105
	v_add_f32_e32 v104, 1.0, v117
	v_rcp_f32_e32 v117, v104
	v_add_f32_e32 v104, 1.0, v110
	v_rcp_f32_e32 v110, v104
	v_mov_b32_e32 v104, v96
	v_mov_b32_e32 v105, v100
	v_pk_mul_f32 v[104:105], v[104:105], v[174:175] op_sel_hi:[1,0]
	v_mul_f32_e32 v100, v109, v117
	v_mul_f32_e32 v96, 0xbfb8aa3b, v105
	v_exp_f32_e32 v96, v96
	v_mul_f32_e32 v108, v108, v100
	v_mov_b32_e32 v100, v97
	v_mul_f32_e32 v107, v107, v110
	v_add_f32_e32 v96, 1.0, v96
	v_rcp_f32_e32 v109, v96
	v_pk_mul_f32 v[96:97], v[100:101], v[174:175] op_sel_hi:[1,0]
	v_mul_f32_e32 v106, v106, v107
	v_mul_f32_e32 v100, 0xbfb8aa3b, v97
	v_exp_f32_e32 v100, v100
	v_mul_f32_e32 v101, v105, v109
	v_mul_f32_e32 v104, v104, v101
	v_mov_b32_e32 v101, v102
	v_add_f32_e32 v100, 1.0, v100
	v_rcp_f32_e32 v105, v100
	v_mov_b32_e32 v100, v98
	v_pk_mul_f32 v[100:101], v[100:101], v[174:175] op_sel_hi:[1,0]
	v_mov_b32_e32 v102, v99
	v_mul_f32_e32 v98, 0xbfb8aa3b, v101
	v_exp_f32_e32 v107, v98
	v_pk_mul_f32 v[98:99], v[102:103], v[174:175] op_sel_hi:[1,0]
	v_mul_f32_e32 v97, v97, v105
	v_mul_f32_e32 v102, 0xbfb8aa3b, v99
	v_exp_f32_e32 v102, v102
	v_add_f32_e32 v103, 1.0, v107
	v_rcp_f32_e32 v103, v103
	v_mul_f32_e32 v105, v96, v97
	v_add_f32_e32 v102, 1.0, v102
	v_rcp_f32_e32 v102, v102
	v_mul_f32_e32 v96, v101, v103
	v_mul_f32_e32 v100, v100, v96
	v_mov_b32_e32 v103, v92
	v_mul_f32_e32 v96, v99, v102
	v_mov_b32_e32 v102, v88
	v_pk_mul_f32 v[102:103], v[102:103], v[172:173] op_sel_hi:[1,0]
	v_mul_f32_e32 v99, v98, v96
	v_mul_f32_e32 v88, 0xbfb8aa3b, v103
	v_cvt_pk_bf16_f32 v96, v116, v111
	v_cvt_pk_bf16_f32 v97, v108, v106
	v_cvt_pk_bf16_f32 v98, v104, v105
	v_exp_f32_e32 v104, v88
	v_mov_b32_e32 v92, v89
	v_pk_mul_f32 v[88:89], v[92:93], v[172:173] op_sel_hi:[1,0]
	v_cvt_pk_bf16_f32 v99, v100, v99
	v_mad_i64_i32 v[100:101], s[4:5], v160, s52, v[112:113]
	v_mul_f32_e32 v92, 0xbfb8aa3b, v89
	v_exp_f32_e32 v105, v92
	v_lshl_add_u64 v[92:93], v[100:101], 0, v[114:115]
	v_add_f32_e32 v100, 1.0, v104
	v_rcp_f32_e32 v100, v100
	global_store_dwordx4 v[92:93], v[96:99], off
	v_mov_b32_e32 v93, v94
	v_add_f32_e32 v101, 1.0, v105
	v_mul_f32_e32 v92, v103, v100
	v_mul_f32_e32 v96, v102, v92
	v_mov_b32_e32 v92, v90
	v_pk_mul_f32 v[92:93], v[92:93], v[172:173] op_sel_hi:[1,0]
	v_mov_b32_e32 v94, v91
	v_mul_f32_e32 v90, 0xbfb8aa3b, v93
	v_rcp_f32_e32 v101, v101
	v_exp_f32_e32 v97, v90
	v_pk_mul_f32 v[90:91], v[94:95], v[172:173] op_sel_hi:[1,0]
	v_mul_f32_e32 v89, v89, v101
	v_mul_f32_e32 v94, 0xbfb8aa3b, v91
	v_exp_f32_e32 v94, v94
	v_mul_f32_e32 v95, v88, v89
	v_add_f32_e32 v88, 1.0, v97
	v_rcp_f32_e32 v97, v88
	v_add_f32_e32 v88, 1.0, v94
	v_rcp_f32_e32 v94, v88
	v_mov_b32_e32 v88, v80
	v_mov_b32_e32 v89, v84
	v_pk_mul_f32 v[88:89], v[88:89], v[172:173] op_sel_hi:[1,0]
	v_mul_f32_e32 v84, v93, v97
	v_mul_f32_e32 v80, 0xbfb8aa3b, v89
	v_exp_f32_e32 v80, v80
	v_mul_f32_e32 v92, v92, v84
	v_mov_b32_e32 v84, v81
	v_mul_f32_e32 v91, v91, v94
	v_add_f32_e32 v80, 1.0, v80
	v_rcp_f32_e32 v93, v80
	v_pk_mul_f32 v[80:81], v[84:85], v[172:173] op_sel_hi:[1,0]
	v_mul_f32_e32 v90, v90, v91
	v_mul_f32_e32 v84, 0xbfb8aa3b, v81
	v_exp_f32_e32 v84, v84
	v_mul_f32_e32 v85, v89, v93
	v_mul_f32_e32 v88, v88, v85
	v_mov_b32_e32 v85, v86
	v_add_f32_e32 v84, 1.0, v84
	v_rcp_f32_e32 v89, v84
	v_mov_b32_e32 v84, v82
	v_pk_mul_f32 v[84:85], v[84:85], v[172:173] op_sel_hi:[1,0]
	v_mov_b32_e32 v86, v83
	v_mul_f32_e32 v82, 0xbfb8aa3b, v85
	v_exp_f32_e32 v91, v82
	v_pk_mul_f32 v[82:83], v[86:87], v[172:173] op_sel_hi:[1,0]
	v_mul_f32_e32 v81, v81, v89
	v_mul_f32_e32 v86, 0xbfb8aa3b, v83
	v_exp_f32_e32 v86, v86
	v_add_f32_e32 v87, 1.0, v91
	v_rcp_f32_e32 v87, v87
	v_mul_f32_e32 v89, v80, v81
	v_add_f32_e32 v86, 1.0, v86
	v_rcp_f32_e32 v86, v86
	v_mul_f32_e32 v80, v85, v87
	v_mul_f32_e32 v84, v84, v80
	v_mov_b32_e32 v87, v76
	v_mul_f32_e32 v80, v83, v86
	v_mov_b32_e32 v86, v72
	v_pk_mul_f32 v[86:87], v[86:87], v[170:171] op_sel_hi:[1,0]
	v_mul_f32_e32 v83, v82, v80
	v_mul_f32_e32 v72, 0xbfb8aa3b, v87
	v_cvt_pk_bf16_f32 v80, v96, v95
	v_cvt_pk_bf16_f32 v81, v92, v90
	v_cvt_pk_bf16_f32 v82, v88, v89
	v_exp_f32_e32 v88, v72
	v_mov_b32_e32 v76, v73
	v_pk_mul_f32 v[72:73], v[76:77], v[170:171] op_sel_hi:[1,0]
	v_cvt_pk_bf16_f32 v83, v84, v83
	v_mad_i64_i32 v[84:85], s[4:5], v156, s52, v[112:113]
	v_mul_f32_e32 v76, 0xbfb8aa3b, v73
	v_exp_f32_e32 v89, v76
	v_lshl_add_u64 v[76:77], v[84:85], 0, v[114:115]
	v_add_f32_e32 v84, 1.0, v88
	v_rcp_f32_e32 v84, v84
	global_store_dwordx4 v[76:77], v[80:83], off
	v_mov_b32_e32 v77, v78
	v_add_f32_e32 v85, 1.0, v89
	v_mul_f32_e32 v76, v87, v84
	v_mul_f32_e32 v80, v86, v76
	v_mov_b32_e32 v76, v74
	v_pk_mul_f32 v[76:77], v[76:77], v[170:171] op_sel_hi:[1,0]
	v_mov_b32_e32 v78, v75
	v_mul_f32_e32 v74, 0xbfb8aa3b, v77
	v_rcp_f32_e32 v85, v85
	v_exp_f32_e32 v81, v74
	v_pk_mul_f32 v[74:75], v[78:79], v[170:171] op_sel_hi:[1,0]
	v_mul_f32_e32 v73, v73, v85
	v_mul_f32_e32 v78, 0xbfb8aa3b, v75
	v_exp_f32_e32 v78, v78
	v_mul_f32_e32 v79, v72, v73
	v_add_f32_e32 v72, 1.0, v81
	v_rcp_f32_e32 v81, v72
	v_add_f32_e32 v72, 1.0, v78
	v_rcp_f32_e32 v78, v72
	v_mov_b32_e32 v72, v64
	v_mov_b32_e32 v73, v68
	v_pk_mul_f32 v[72:73], v[72:73], v[170:171] op_sel_hi:[1,0]
	v_mul_f32_e32 v68, v77, v81
	v_mul_f32_e32 v64, 0xbfb8aa3b, v73
	v_exp_f32_e32 v64, v64
	v_mul_f32_e32 v76, v76, v68
	v_mov_b32_e32 v68, v65
	v_mul_f32_e32 v75, v75, v78
	v_add_f32_e32 v64, 1.0, v64
	v_rcp_f32_e32 v77, v64
	v_pk_mul_f32 v[64:65], v[68:69], v[170:171] op_sel_hi:[1,0]
	v_mul_f32_e32 v74, v74, v75
	v_mul_f32_e32 v68, 0xbfb8aa3b, v65
	v_exp_f32_e32 v68, v68
	v_mul_f32_e32 v69, v73, v77
	v_mul_f32_e32 v72, v72, v69
	v_mov_b32_e32 v69, v70
	v_add_f32_e32 v68, 1.0, v68
	v_rcp_f32_e32 v73, v68
	v_mov_b32_e32 v68, v66
	v_pk_mul_f32 v[68:69], v[68:69], v[170:171] op_sel_hi:[1,0]
	v_mov_b32_e32 v70, v67
	v_mul_f32_e32 v66, 0xbfb8aa3b, v69
	v_exp_f32_e32 v75, v66
	v_pk_mul_f32 v[66:67], v[70:71], v[170:171] op_sel_hi:[1,0]
	v_mul_f32_e32 v65, v65, v73
	v_mul_f32_e32 v70, 0xbfb8aa3b, v67
	v_exp_f32_e32 v70, v70
	v_add_f32_e32 v71, 1.0, v75
	v_rcp_f32_e32 v71, v71
	v_mul_f32_e32 v73, v64, v65
	v_add_f32_e32 v70, 1.0, v70
	v_rcp_f32_e32 v70, v70
	v_mul_f32_e32 v64, v69, v71
	v_mul_f32_e32 v68, v68, v64
	v_mov_b32_e32 v71, v60
	v_mul_f32_e32 v64, v67, v70
	v_mov_b32_e32 v70, v56
	v_pk_mul_f32 v[70:71], v[70:71], v[168:169] op_sel_hi:[1,0]
	v_mul_f32_e32 v67, v66, v64
	v_mul_f32_e32 v56, 0xbfb8aa3b, v71
	v_cvt_pk_bf16_f32 v64, v80, v79
	v_cvt_pk_bf16_f32 v65, v76, v74
	v_cvt_pk_bf16_f32 v66, v72, v73
	v_exp_f32_e32 v72, v56
	v_mov_b32_e32 v60, v57
	v_pk_mul_f32 v[56:57], v[60:61], v[168:169] op_sel_hi:[1,0]
	v_cvt_pk_bf16_f32 v67, v68, v67
	v_mad_i64_i32 v[68:69], s[4:5], v154, s52, v[112:113]
	v_mul_f32_e32 v60, 0xbfb8aa3b, v57
	v_exp_f32_e32 v73, v60
	v_lshl_add_u64 v[60:61], v[68:69], 0, v[114:115]
	v_add_f32_e32 v68, 1.0, v72
	v_rcp_f32_e32 v68, v68
	global_store_dwordx4 v[60:61], v[64:67], off
	v_mov_b32_e32 v61, v62
	v_add_f32_e32 v69, 1.0, v73
	v_mul_f32_e32 v60, v71, v68
	v_mul_f32_e32 v64, v70, v60
	v_mov_b32_e32 v60, v58
	v_pk_mul_f32 v[60:61], v[60:61], v[168:169] op_sel_hi:[1,0]
	v_mov_b32_e32 v62, v59
	v_mul_f32_e32 v58, 0xbfb8aa3b, v61
	v_rcp_f32_e32 v69, v69
	v_exp_f32_e32 v65, v58
	v_pk_mul_f32 v[58:59], v[62:63], v[168:169] op_sel_hi:[1,0]
	v_mul_f32_e32 v57, v57, v69
	v_mul_f32_e32 v62, 0xbfb8aa3b, v59
	v_exp_f32_e32 v62, v62
	v_mul_f32_e32 v63, v56, v57
	v_add_f32_e32 v56, 1.0, v65
	v_rcp_f32_e32 v65, v56
	v_add_f32_e32 v56, 1.0, v62
	v_rcp_f32_e32 v62, v56
	v_mov_b32_e32 v56, v48
	v_mov_b32_e32 v57, v52
	v_pk_mul_f32 v[56:57], v[56:57], v[168:169] op_sel_hi:[1,0]
	v_mul_f32_e32 v52, v61, v65
	v_mul_f32_e32 v48, 0xbfb8aa3b, v57
	v_exp_f32_e32 v48, v48
	v_mul_f32_e32 v60, v60, v52
	v_mov_b32_e32 v52, v49
	v_mul_f32_e32 v59, v59, v62
	v_add_f32_e32 v48, 1.0, v48
	v_rcp_f32_e32 v61, v48
	v_pk_mul_f32 v[48:49], v[52:53], v[168:169] op_sel_hi:[1,0]
	v_mul_f32_e32 v58, v58, v59
	v_mul_f32_e32 v52, 0xbfb8aa3b, v49
	v_exp_f32_e32 v52, v52
	v_mul_f32_e32 v53, v57, v61
	v_mul_f32_e32 v56, v56, v53
	v_mov_b32_e32 v53, v54
	v_add_f32_e32 v52, 1.0, v52
	v_rcp_f32_e32 v57, v52
	v_mov_b32_e32 v52, v50
	v_pk_mul_f32 v[52:53], v[52:53], v[168:169] op_sel_hi:[1,0]
	v_mov_b32_e32 v54, v51
	v_mul_f32_e32 v50, 0xbfb8aa3b, v53
	v_exp_f32_e32 v59, v50
	v_pk_mul_f32 v[50:51], v[54:55], v[168:169] op_sel_hi:[1,0]
	v_mul_f32_e32 v49, v49, v57
	v_mul_f32_e32 v54, 0xbfb8aa3b, v51
	v_exp_f32_e32 v54, v54
	v_add_f32_e32 v55, 1.0, v59
	v_rcp_f32_e32 v55, v55
	v_mul_f32_e32 v57, v48, v49
	v_add_f32_e32 v54, 1.0, v54
	v_rcp_f32_e32 v54, v54
	v_mul_f32_e32 v48, v53, v55
	v_mul_f32_e32 v52, v52, v48
	v_mov_b32_e32 v55, v44
	v_mul_f32_e32 v48, v51, v54
	v_mov_b32_e32 v54, v40
	v_pk_mul_f32 v[54:55], v[54:55], v[166:167] op_sel_hi:[1,0]
	v_mul_f32_e32 v51, v50, v48
	v_mul_f32_e32 v40, 0xbfb8aa3b, v55
	v_cvt_pk_bf16_f32 v48, v64, v63
	v_cvt_pk_bf16_f32 v49, v60, v58
	v_cvt_pk_bf16_f32 v50, v56, v57
	v_exp_f32_e32 v56, v40
	v_mov_b32_e32 v44, v41
	v_pk_mul_f32 v[40:41], v[44:45], v[166:167] op_sel_hi:[1,0]
	v_cvt_pk_bf16_f32 v51, v52, v51
	v_mad_i64_i32 v[52:53], s[4:5], v148, s52, v[112:113]
	v_mul_f32_e32 v44, 0xbfb8aa3b, v41
	v_exp_f32_e32 v57, v44
	v_lshl_add_u64 v[44:45], v[52:53], 0, v[114:115]
	v_add_f32_e32 v52, 1.0, v56
	v_rcp_f32_e32 v52, v52
	global_store_dwordx4 v[44:45], v[48:51], off
	v_mov_b32_e32 v45, v46
	v_add_f32_e32 v53, 1.0, v57
	v_mul_f32_e32 v44, v55, v52
	v_mul_f32_e32 v48, v54, v44
	v_mov_b32_e32 v44, v42
	v_pk_mul_f32 v[44:45], v[44:45], v[166:167] op_sel_hi:[1,0]
	v_mov_b32_e32 v46, v43
	v_mul_f32_e32 v42, 0xbfb8aa3b, v45
	v_rcp_f32_e32 v53, v53
	v_exp_f32_e32 v49, v42
	v_pk_mul_f32 v[42:43], v[46:47], v[166:167] op_sel_hi:[1,0]
	v_mul_f32_e32 v41, v41, v53
	v_mul_f32_e32 v46, 0xbfb8aa3b, v43
	v_exp_f32_e32 v46, v46
	v_mul_f32_e32 v47, v40, v41
	v_add_f32_e32 v40, 1.0, v49
	v_rcp_f32_e32 v49, v40
	v_add_f32_e32 v40, 1.0, v46
	v_rcp_f32_e32 v46, v40
	v_mov_b32_e32 v40, v32
	v_mov_b32_e32 v41, v36
	v_pk_mul_f32 v[40:41], v[40:41], v[166:167] op_sel_hi:[1,0]
	v_mul_f32_e32 v36, v45, v49
	v_mul_f32_e32 v32, 0xbfb8aa3b, v41
	v_exp_f32_e32 v32, v32
	v_mul_f32_e32 v44, v44, v36
	v_mov_b32_e32 v36, v33
	v_mul_f32_e32 v43, v43, v46
	v_add_f32_e32 v32, 1.0, v32
	v_rcp_f32_e32 v45, v32
	v_pk_mul_f32 v[32:33], v[36:37], v[166:167] op_sel_hi:[1,0]
	v_mul_f32_e32 v42, v42, v43
	v_mul_f32_e32 v36, 0xbfb8aa3b, v33
	v_exp_f32_e32 v36, v36
	v_mul_f32_e32 v37, v41, v45
	v_mul_f32_e32 v40, v40, v37
	v_mov_b32_e32 v37, v38
	v_add_f32_e32 v36, 1.0, v36
	v_rcp_f32_e32 v41, v36
	v_mov_b32_e32 v36, v34
	v_pk_mul_f32 v[36:37], v[36:37], v[166:167] op_sel_hi:[1,0]
	v_mov_b32_e32 v38, v35
	v_mul_f32_e32 v34, 0xbfb8aa3b, v37
	v_exp_f32_e32 v43, v34
	v_pk_mul_f32 v[34:35], v[38:39], v[166:167] op_sel_hi:[1,0]
	v_mul_f32_e32 v33, v33, v41
	v_mul_f32_e32 v38, 0xbfb8aa3b, v35
	v_exp_f32_e32 v38, v38
	v_add_f32_e32 v39, 1.0, v43
	v_rcp_f32_e32 v39, v39
	v_mul_f32_e32 v41, v32, v33
	v_add_f32_e32 v38, 1.0, v38
	v_rcp_f32_e32 v38, v38
	v_mul_f32_e32 v32, v37, v39
	v_mul_f32_e32 v36, v36, v32
	v_mov_b32_e32 v39, v28
	v_mul_f32_e32 v32, v35, v38
	v_mov_b32_e32 v38, v24
	v_pk_mul_f32 v[38:39], v[38:39], v[164:165] op_sel_hi:[1,0]
	v_mul_f32_e32 v35, v34, v32
	v_mul_f32_e32 v24, 0xbfb8aa3b, v39
	v_cvt_pk_bf16_f32 v32, v48, v47
	v_cvt_pk_bf16_f32 v33, v44, v42
	v_cvt_pk_bf16_f32 v34, v40, v41
	v_exp_f32_e32 v40, v24
	v_mov_b32_e32 v28, v25
	v_pk_mul_f32 v[24:25], v[28:29], v[164:165] op_sel_hi:[1,0]
	v_cvt_pk_bf16_f32 v35, v36, v35
	v_mad_i64_i32 v[36:37], s[4:5], v152, s52, v[112:113]
	v_mul_f32_e32 v28, 0xbfb8aa3b, v25
	v_exp_f32_e32 v41, v28
	v_lshl_add_u64 v[28:29], v[36:37], 0, v[114:115]
	v_add_f32_e32 v36, 1.0, v40
	v_rcp_f32_e32 v36, v36
	global_store_dwordx4 v[28:29], v[32:35], off
	v_mov_b32_e32 v29, v30
	v_add_f32_e32 v37, 1.0, v41
	v_mul_f32_e32 v28, v39, v36
	v_mul_f32_e32 v32, v38, v28
	v_mov_b32_e32 v28, v26
	v_pk_mul_f32 v[28:29], v[28:29], v[164:165] op_sel_hi:[1,0]
	v_mov_b32_e32 v30, v27
	v_mul_f32_e32 v26, 0xbfb8aa3b, v29
	v_rcp_f32_e32 v37, v37
	v_exp_f32_e32 v33, v26
	v_pk_mul_f32 v[26:27], v[30:31], v[164:165] op_sel_hi:[1,0]
	v_mul_f32_e32 v25, v25, v37
	v_mul_f32_e32 v30, 0xbfb8aa3b, v27
	v_exp_f32_e32 v30, v30
	v_mul_f32_e32 v31, v24, v25
	v_add_f32_e32 v24, 1.0, v33
	v_rcp_f32_e32 v33, v24
	v_add_f32_e32 v24, 1.0, v30
	v_rcp_f32_e32 v30, v24
	v_mov_b32_e32 v24, v16
	v_mov_b32_e32 v25, v20
	v_pk_mul_f32 v[24:25], v[24:25], v[164:165] op_sel_hi:[1,0]
	v_mul_f32_e32 v20, v29, v33
	v_mul_f32_e32 v16, 0xbfb8aa3b, v25
	v_exp_f32_e32 v16, v16
	v_mul_f32_e32 v28, v28, v20
	v_mov_b32_e32 v20, v17
	v_mul_f32_e32 v27, v27, v30
	v_add_f32_e32 v16, 1.0, v16
	v_rcp_f32_e32 v29, v16
	v_pk_mul_f32 v[16:17], v[20:21], v[164:165] op_sel_hi:[1,0]
	v_mul_f32_e32 v26, v26, v27
	v_mul_f32_e32 v20, 0xbfb8aa3b, v17
	v_exp_f32_e32 v20, v20
	v_mul_f32_e32 v21, v25, v29
	v_mul_f32_e32 v24, v24, v21
	v_mov_b32_e32 v21, v22
	v_add_f32_e32 v20, 1.0, v20
	v_rcp_f32_e32 v25, v20
	v_mov_b32_e32 v20, v18
	v_pk_mul_f32 v[20:21], v[20:21], v[164:165] op_sel_hi:[1,0]
	v_mov_b32_e32 v22, v19
	v_mul_f32_e32 v18, 0xbfb8aa3b, v21
	v_exp_f32_e32 v27, v18
	v_pk_mul_f32 v[18:19], v[22:23], v[164:165] op_sel_hi:[1,0]
	v_mul_f32_e32 v17, v17, v25
	v_mul_f32_e32 v22, 0xbfb8aa3b, v19
	v_exp_f32_e32 v22, v22
	v_add_f32_e32 v23, 1.0, v27
	v_rcp_f32_e32 v23, v23
	v_mul_f32_e32 v25, v16, v17
	v_add_f32_e32 v22, 1.0, v22
	v_rcp_f32_e32 v22, v22
	v_mul_f32_e32 v16, v21, v23
	v_mul_f32_e32 v20, v20, v16
	v_mov_b32_e32 v23, v12
	v_mul_f32_e32 v16, v19, v22
	v_mov_b32_e32 v22, v8
	v_pk_mul_f32 v[22:23], v[22:23], v[158:159] op_sel_hi:[1,0]
	v_mul_f32_e32 v19, v18, v16
	v_mul_f32_e32 v8, 0xbfb8aa3b, v23
	v_cvt_pk_bf16_f32 v16, v32, v31
	v_cvt_pk_bf16_f32 v17, v28, v26
	v_cvt_pk_bf16_f32 v18, v24, v25
	v_exp_f32_e32 v24, v8
	v_mov_b32_e32 v12, v9
	v_pk_mul_f32 v[8:9], v[12:13], v[158:159] op_sel_hi:[1,0]
	v_cvt_pk_bf16_f32 v19, v20, v19
	v_mad_i64_i32 v[20:21], s[4:5], v150, s52, v[112:113]
	v_mul_f32_e32 v12, 0xbfb8aa3b, v9
	v_exp_f32_e32 v25, v12
	v_lshl_add_u64 v[12:13], v[20:21], 0, v[114:115]
	v_add_f32_e32 v20, 1.0, v24
	v_rcp_f32_e32 v20, v20
	global_store_dwordx4 v[12:13], v[16:19], off
	v_mov_b32_e32 v13, v14
	v_add_f32_e32 v21, 1.0, v25
	v_mul_f32_e32 v12, v23, v20
	v_mul_f32_e32 v16, v22, v12
	v_mov_b32_e32 v12, v10
	v_pk_mul_f32 v[12:13], v[12:13], v[158:159] op_sel_hi:[1,0]
	v_mov_b32_e32 v14, v11
	v_mul_f32_e32 v10, 0xbfb8aa3b, v13
	v_rcp_f32_e32 v21, v21
	v_exp_f32_e32 v17, v10
	v_pk_mul_f32 v[10:11], v[14:15], v[158:159] op_sel_hi:[1,0]
	v_mul_f32_e32 v9, v9, v21
	v_mul_f32_e32 v14, 0xbfb8aa3b, v11
	v_exp_f32_e32 v14, v14
	v_mul_f32_e32 v15, v8, v9
	v_add_f32_e32 v8, 1.0, v17
	v_rcp_f32_e32 v17, v8
	v_add_f32_e32 v8, 1.0, v14
	v_rcp_f32_e32 v14, v8
	v_mov_b32_e32 v8, v0
	v_mov_b32_e32 v9, v4
	v_pk_mul_f32 v[8:9], v[8:9], v[158:159] op_sel_hi:[1,0]
	v_mul_f32_e32 v4, v13, v17
	v_mul_f32_e32 v0, 0xbfb8aa3b, v9
	v_exp_f32_e32 v0, v0
	v_mul_f32_e32 v12, v12, v4
	v_mov_b32_e32 v4, v1
	v_mul_f32_e32 v11, v11, v14
	v_add_f32_e32 v0, 1.0, v0
	v_rcp_f32_e32 v13, v0
	v_pk_mul_f32 v[0:1], v[4:5], v[158:159] op_sel_hi:[1,0]
	v_mul_f32_e32 v10, v10, v11
	v_mul_f32_e32 v4, 0xbfb8aa3b, v1
	v_exp_f32_e32 v4, v4
	v_mul_f32_e32 v5, v9, v13
	v_mul_f32_e32 v8, v8, v5
	v_mov_b32_e32 v5, v6
	v_add_f32_e32 v4, 1.0, v4
	v_rcp_f32_e32 v9, v4
	v_mov_b32_e32 v4, v2
	v_pk_mul_f32 v[4:5], v[4:5], v[158:159] op_sel_hi:[1,0]
	v_mov_b32_e32 v6, v3
	v_mul_f32_e32 v2, 0xbfb8aa3b, v5
	v_exp_f32_e32 v11, v2
	v_pk_mul_f32 v[2:3], v[6:7], v[158:159] op_sel_hi:[1,0]
	v_mul_f32_e32 v1, v1, v9
	v_mul_f32_e32 v6, 0xbfb8aa3b, v3
	v_exp_f32_e32 v6, v6
	v_add_f32_e32 v7, 1.0, v11
	v_rcp_f32_e32 v7, v7
	v_mul_f32_e32 v9, v0, v1
	v_add_f32_e32 v6, 1.0, v6
	v_rcp_f32_e32 v6, v6
	v_mul_f32_e32 v0, v5, v7
	v_mul_f32_e32 v4, v4, v0
	v_mul_f32_e32 v0, v3, v6
	v_mul_f32_e32 v3, v2, v0
	v_cvt_pk_bf16_f32 v0, v16, v15
	v_cvt_pk_bf16_f32 v1, v12, v10
	v_cvt_pk_bf16_f32 v2, v8, v9
	v_cvt_pk_bf16_f32 v3, v4, v3
	v_mad_i64_i32 v[4:5], s[4:5], v146, s52, v[112:113]
	v_lshl_add_u64 v[4:5], v[4:5], 0, v[114:115]
	s_mov_b64 s[4:5], -1
	global_store_dwordx4 v[4:5], v[0:3], off
	s_cbranch_vccnz .LBB0_479
	s_andn2_b64 vcc, exec, s[16:17]
	s_cbranch_vccnz .LBB0_478
	s_mov_b32 s90, 1
	s_branch .LBB0_478

.Lrstd_done_p9:
	v_or_b32_e32 v160, 16, v162
	v_or_b32_e32 v156, 32, v162
	v_or_b32_e32 v154, 48, v162
	v_add_u32_e32 v148, 0x80, v162
	v_add_u32_e32 v152, 0x90, v162
	v_add_u32_e32 v150, 0xa0, v162
	v_add_u32_e32 v146, 0xb0, v162
	v_mov_b32_e32 v178, v120
	v_mov_b32_e32 v179, v124
	v_pk_mul_f32 v[178:179], v[178:179], v[176:177] op_sel_hi:[1,0]
	v_mov_b32_e32 v124, v121
	v_mul_f32_e32 v120, 0xbfb8aa3b, v179
	v_exp_f32_e32 v147, v120
	v_pk_mul_f32 v[120:121], v[124:125], v[176:177] op_sel_hi:[1,0]
	s_andn2_b64 vcc, exec, s[6:7]
	v_mul_f32_e32 v124, 0xbfb8aa3b, v121
	v_exp_f32_e32 v125, v124
	v_add_f32_e32 v147, 1.0, v147
	v_rcp_f32_e32 v147, v147
	v_lshl_or_b32 v124, s33, 7, v167
	v_add_f32_e32 v125, 1.0, v125
	v_rcp_f32_e32 v149, v125
	v_mul_f32_e32 v147, v179, v147
	v_mul_f32_e32 v147, v178, v147
	v_mov_b32_e32 v178, v122
	v_mov_b32_e32 v179, v126
	v_pk_mul_f32 v[178:179], v[178:179], v[176:177] op_sel_hi:[1,0]
	v_mov_b32_e32 v126, v123
	v_mul_f32_e32 v122, 0xbfb8aa3b, v179
	v_mul_f32_e32 v121, v121, v149
	v_exp_f32_e32 v149, v122
	v_pk_mul_f32 v[122:123], v[126:127], v[176:177] op_sel_hi:[1,0]
	v_mul_f32_e32 v127, v120, v121
	v_mul_f32_e32 v126, 0xbfb8aa3b, v123
	v_exp_f32_e32 v126, v126
	v_add_f32_e32 v120, 1.0, v149
	v_rcp_f32_e32 v149, v120
	v_mov_b32_e32 v121, v116
	v_add_f32_e32 v120, 1.0, v126
	v_rcp_f32_e32 v126, v120
	v_mov_b32_e32 v120, v112
	v_pk_mul_f32 v[120:121], v[120:121], v[176:177] op_sel_hi:[1,0]
	v_mul_f32_e32 v116, v179, v149
	v_mul_f32_e32 v112, 0xbfb8aa3b, v121
	v_exp_f32_e32 v112, v112
	v_mul_f32_e32 v149, v178, v116
	v_mov_b32_e32 v116, v113
	v_mul_f32_e32 v123, v123, v126
	v_add_f32_e32 v112, 1.0, v112
	v_rcp_f32_e32 v126, v112
	v_pk_mul_f32 v[112:113], v[116:117], v[176:177] op_sel_hi:[1,0]
	v_mul_f32_e32 v122, v122, v123
	v_mul_f32_e32 v116, 0xbfb8aa3b, v113
	v_exp_f32_e32 v116, v116
	v_mul_f32_e32 v117, v121, v126
	v_mul_f32_e32 v120, v120, v117
	v_mov_b32_e32 v117, v118
	v_add_f32_e32 v116, 1.0, v116
	v_rcp_f32_e32 v121, v116
	v_mov_b32_e32 v116, v114
	v_pk_mul_f32 v[116:117], v[116:117], v[176:177] op_sel_hi:[1,0]
	v_mov_b32_e32 v118, v115
	v_mul_f32_e32 v114, 0xbfb8aa3b, v117
	v_exp_f32_e32 v123, v114
	v_pk_mul_f32 v[114:115], v[118:119], v[176:177] op_sel_hi:[1,0]
	v_mul_f32_e32 v113, v113, v121
	v_mul_f32_e32 v118, 0xbfb8aa3b, v115
	v_exp_f32_e32 v118, v118
	v_add_f32_e32 v119, 1.0, v123
	v_rcp_f32_e32 v119, v119
	v_mul_f32_e32 v112, v112, v113
	v_add_f32_e32 v118, 1.0, v118
	v_rcp_f32_e32 v118, v118
	v_mul_f32_e32 v113, v117, v119
	v_mul_f32_e32 v113, v116, v113
	v_cvt_pk_bf16_f32 v116, v147, v127
	v_cvt_pk_bf16_f32 v117, v149, v122
	v_mov_b32_e32 v122, v104
	v_mov_b32_e32 v123, v108
	v_mul_f32_e32 v115, v115, v118
	v_pk_mul_f32 v[122:123], v[122:123], v[174:175] op_sel_hi:[1,0]
	v_ashrrev_i32_e32 v125, 31, v124
	v_mul_f32_e32 v114, v114, v115
	v_mul_f32_e32 v104, 0xbfb8aa3b, v123
	v_cvt_pk_bf16_f32 v118, v120, v112
	v_cvt_pk_bf16_f32 v119, v113, v114
	v_lshlrev_b64 v[114:115], 1, v[124:125]
	v_exp_f32_e32 v124, v104
	v_mov_b32_e32 v108, v105
	v_mov_b64_e32 v[112:113], s[22:23]
	v_pk_mul_f32 v[104:105], v[108:109], v[174:175] op_sel_hi:[1,0]
	v_mad_i64_i32 v[120:121], s[4:5], v162, s51, v[112:113]
	v_mul_f32_e32 v108, 0xbfb8aa3b, v105
	v_exp_f32_e32 v125, v108
	v_lshl_add_u64 v[108:109], v[120:121], 0, v[114:115]
	v_add_f32_e32 v120, 1.0, v124
	v_rcp_f32_e32 v120, v120
	global_store_dwordx4 v[108:109], v[116:119], off
	v_mov_b32_e32 v109, v110
	v_add_f32_e32 v121, 1.0, v125
	v_mul_f32_e32 v108, v123, v120
	v_mul_f32_e32 v116, v122, v108
	v_mov_b32_e32 v108, v106
	v_pk_mul_f32 v[108:109], v[108:109], v[174:175] op_sel_hi:[1,0]
	v_mov_b32_e32 v110, v107
	v_mul_f32_e32 v106, 0xbfb8aa3b, v109
	v_rcp_f32_e32 v121, v121
	v_exp_f32_e32 v117, v106
	v_pk_mul_f32 v[106:107], v[110:111], v[174:175] op_sel_hi:[1,0]
	v_mul_f32_e32 v105, v105, v121
	v_mul_f32_e32 v110, 0xbfb8aa3b, v107
	v_exp_f32_e32 v110, v110
	v_mul_f32_e32 v111, v104, v105
	v_add_f32_e32 v104, 1.0, v117
	v_rcp_f32_e32 v117, v104
	v_add_f32_e32 v104, 1.0, v110
	v_rcp_f32_e32 v110, v104
	v_mov_b32_e32 v104, v96
	v_mov_b32_e32 v105, v100
	v_pk_mul_f32 v[104:105], v[104:105], v[174:175] op_sel_hi:[1,0]
	v_mul_f32_e32 v100, v109, v117
	v_mul_f32_e32 v96, 0xbfb8aa3b, v105
	v_exp_f32_e32 v96, v96
	v_mul_f32_e32 v108, v108, v100
	v_mov_b32_e32 v100, v97
	v_mul_f32_e32 v107, v107, v110
	v_add_f32_e32 v96, 1.0, v96
	v_rcp_f32_e32 v109, v96
	v_pk_mul_f32 v[96:97], v[100:101], v[174:175] op_sel_hi:[1,0]
	v_mul_f32_e32 v106, v106, v107
	v_mul_f32_e32 v100, 0xbfb8aa3b, v97
	v_exp_f32_e32 v100, v100
	v_mul_f32_e32 v101, v105, v109
	v_mul_f32_e32 v104, v104, v101
	v_mov_b32_e32 v101, v102
	v_add_f32_e32 v100, 1.0, v100
	v_rcp_f32_e32 v105, v100
	v_mov_b32_e32 v100, v98
	v_pk_mul_f32 v[100:101], v[100:101], v[174:175] op_sel_hi:[1,0]
	v_mov_b32_e32 v102, v99
	v_mul_f32_e32 v98, 0xbfb8aa3b, v101
	v_exp_f32_e32 v107, v98
	v_pk_mul_f32 v[98:99], v[102:103], v[174:175] op_sel_hi:[1,0]
	v_mul_f32_e32 v97, v97, v105
	v_mul_f32_e32 v102, 0xbfb8aa3b, v99
	v_exp_f32_e32 v102, v102
	v_add_f32_e32 v103, 1.0, v107
	v_rcp_f32_e32 v103, v103
	v_mul_f32_e32 v105, v96, v97
	v_add_f32_e32 v102, 1.0, v102
	v_rcp_f32_e32 v102, v102
	v_mul_f32_e32 v96, v101, v103
	v_mul_f32_e32 v100, v100, v96
	v_mov_b32_e32 v103, v92
	v_mul_f32_e32 v96, v99, v102
	v_mov_b32_e32 v102, v88
	v_pk_mul_f32 v[102:103], v[102:103], v[172:173] op_sel_hi:[1,0]
	v_mul_f32_e32 v99, v98, v96
	v_mul_f32_e32 v88, 0xbfb8aa3b, v103
	v_cvt_pk_bf16_f32 v96, v116, v111
	v_cvt_pk_bf16_f32 v97, v108, v106
	v_cvt_pk_bf16_f32 v98, v104, v105
	v_exp_f32_e32 v104, v88
	v_mov_b32_e32 v92, v89
	v_pk_mul_f32 v[88:89], v[92:93], v[172:173] op_sel_hi:[1,0]
	v_cvt_pk_bf16_f32 v99, v100, v99
	v_mad_i64_i32 v[100:101], s[4:5], v160, s51, v[112:113]
	v_mul_f32_e32 v92, 0xbfb8aa3b, v89
	v_exp_f32_e32 v105, v92
	v_lshl_add_u64 v[92:93], v[100:101], 0, v[114:115]
	v_add_f32_e32 v100, 1.0, v104
	v_rcp_f32_e32 v100, v100
	global_store_dwordx4 v[92:93], v[96:99], off
	v_mov_b32_e32 v93, v94
	v_add_f32_e32 v101, 1.0, v105
	v_mul_f32_e32 v92, v103, v100
	v_mul_f32_e32 v96, v102, v92
	v_mov_b32_e32 v92, v90
	v_pk_mul_f32 v[92:93], v[92:93], v[172:173] op_sel_hi:[1,0]
	v_mov_b32_e32 v94, v91
	v_mul_f32_e32 v90, 0xbfb8aa3b, v93
	v_rcp_f32_e32 v101, v101
	v_exp_f32_e32 v97, v90
	v_pk_mul_f32 v[90:91], v[94:95], v[172:173] op_sel_hi:[1,0]
	v_mul_f32_e32 v89, v89, v101
	v_mul_f32_e32 v94, 0xbfb8aa3b, v91
	v_exp_f32_e32 v94, v94
	v_mul_f32_e32 v95, v88, v89
	v_add_f32_e32 v88, 1.0, v97
	v_rcp_f32_e32 v97, v88
	v_add_f32_e32 v88, 1.0, v94
	v_rcp_f32_e32 v94, v88
	v_mov_b32_e32 v88, v80
	v_mov_b32_e32 v89, v84
	v_pk_mul_f32 v[88:89], v[88:89], v[172:173] op_sel_hi:[1,0]
	v_mul_f32_e32 v84, v93, v97
	v_mul_f32_e32 v80, 0xbfb8aa3b, v89
	v_exp_f32_e32 v80, v80
	v_mul_f32_e32 v92, v92, v84
	v_mov_b32_e32 v84, v81
	v_mul_f32_e32 v91, v91, v94
	v_add_f32_e32 v80, 1.0, v80
	v_rcp_f32_e32 v93, v80
	v_pk_mul_f32 v[80:81], v[84:85], v[172:173] op_sel_hi:[1,0]
	v_mul_f32_e32 v90, v90, v91
	v_mul_f32_e32 v84, 0xbfb8aa3b, v81
	v_exp_f32_e32 v84, v84
	v_mul_f32_e32 v85, v89, v93
	v_mul_f32_e32 v88, v88, v85
	v_mov_b32_e32 v85, v86
	v_add_f32_e32 v84, 1.0, v84
	v_rcp_f32_e32 v89, v84
	v_mov_b32_e32 v84, v82
	v_pk_mul_f32 v[84:85], v[84:85], v[172:173] op_sel_hi:[1,0]
	v_mov_b32_e32 v86, v83
	v_mul_f32_e32 v82, 0xbfb8aa3b, v85
	v_exp_f32_e32 v91, v82
	v_pk_mul_f32 v[82:83], v[86:87], v[172:173] op_sel_hi:[1,0]
	v_mul_f32_e32 v81, v81, v89
	v_mul_f32_e32 v86, 0xbfb8aa3b, v83
	v_exp_f32_e32 v86, v86
	v_add_f32_e32 v87, 1.0, v91
	v_rcp_f32_e32 v87, v87
	v_mul_f32_e32 v89, v80, v81
	v_add_f32_e32 v86, 1.0, v86
	v_rcp_f32_e32 v86, v86
	v_mul_f32_e32 v80, v85, v87
	v_mul_f32_e32 v84, v84, v80
	v_mov_b32_e32 v87, v76
	v_mul_f32_e32 v80, v83, v86
	v_mov_b32_e32 v86, v72
	v_pk_mul_f32 v[86:87], v[86:87], v[170:171] op_sel_hi:[1,0]
	v_mul_f32_e32 v83, v82, v80
	v_mul_f32_e32 v72, 0xbfb8aa3b, v87
	v_cvt_pk_bf16_f32 v80, v96, v95
	v_cvt_pk_bf16_f32 v81, v92, v90
	v_cvt_pk_bf16_f32 v82, v88, v89
	v_exp_f32_e32 v88, v72
	v_mov_b32_e32 v76, v73
	v_pk_mul_f32 v[72:73], v[76:77], v[170:171] op_sel_hi:[1,0]
	v_cvt_pk_bf16_f32 v83, v84, v83
	v_mad_i64_i32 v[84:85], s[4:5], v156, s51, v[112:113]
	v_mul_f32_e32 v76, 0xbfb8aa3b, v73
	v_exp_f32_e32 v89, v76
	v_lshl_add_u64 v[76:77], v[84:85], 0, v[114:115]
	v_add_f32_e32 v84, 1.0, v88
	v_rcp_f32_e32 v84, v84
	global_store_dwordx4 v[76:77], v[80:83], off
	v_mov_b32_e32 v77, v78
	v_add_f32_e32 v85, 1.0, v89
	v_mul_f32_e32 v76, v87, v84
	v_mul_f32_e32 v80, v86, v76
	v_mov_b32_e32 v76, v74
	v_pk_mul_f32 v[76:77], v[76:77], v[170:171] op_sel_hi:[1,0]
	v_mov_b32_e32 v78, v75
	v_mul_f32_e32 v74, 0xbfb8aa3b, v77
	v_rcp_f32_e32 v85, v85
	v_exp_f32_e32 v81, v74
	v_pk_mul_f32 v[74:75], v[78:79], v[170:171] op_sel_hi:[1,0]
	v_mul_f32_e32 v73, v73, v85
	v_mul_f32_e32 v78, 0xbfb8aa3b, v75
	v_exp_f32_e32 v78, v78
	v_mul_f32_e32 v79, v72, v73
	v_add_f32_e32 v72, 1.0, v81
	v_rcp_f32_e32 v81, v72
	v_add_f32_e32 v72, 1.0, v78
	v_rcp_f32_e32 v78, v72
	v_mov_b32_e32 v72, v64
	v_mov_b32_e32 v73, v68
	v_pk_mul_f32 v[72:73], v[72:73], v[170:171] op_sel_hi:[1,0]
	v_mul_f32_e32 v68, v77, v81
	v_mul_f32_e32 v64, 0xbfb8aa3b, v73
	v_exp_f32_e32 v64, v64
	v_mul_f32_e32 v76, v76, v68
	v_mov_b32_e32 v68, v65
	v_mul_f32_e32 v75, v75, v78
	v_add_f32_e32 v64, 1.0, v64
	v_rcp_f32_e32 v77, v64
	v_pk_mul_f32 v[64:65], v[68:69], v[170:171] op_sel_hi:[1,0]
	v_mul_f32_e32 v74, v74, v75
	v_mul_f32_e32 v68, 0xbfb8aa3b, v65
	v_exp_f32_e32 v68, v68
	v_mul_f32_e32 v69, v73, v77
	v_mul_f32_e32 v72, v72, v69
	v_mov_b32_e32 v69, v70
	v_add_f32_e32 v68, 1.0, v68
	v_rcp_f32_e32 v73, v68
	v_mov_b32_e32 v68, v66
	v_pk_mul_f32 v[68:69], v[68:69], v[170:171] op_sel_hi:[1,0]
	v_mov_b32_e32 v70, v67
	v_mul_f32_e32 v66, 0xbfb8aa3b, v69
	v_exp_f32_e32 v75, v66
	v_pk_mul_f32 v[66:67], v[70:71], v[170:171] op_sel_hi:[1,0]
	v_mul_f32_e32 v65, v65, v73
	v_mul_f32_e32 v70, 0xbfb8aa3b, v67
	v_exp_f32_e32 v70, v70
	v_add_f32_e32 v71, 1.0, v75
	v_rcp_f32_e32 v71, v71
	v_mul_f32_e32 v73, v64, v65
	v_add_f32_e32 v70, 1.0, v70
	v_rcp_f32_e32 v70, v70
	v_mul_f32_e32 v64, v69, v71
	v_mul_f32_e32 v68, v68, v64
	v_mov_b32_e32 v71, v60
	v_mul_f32_e32 v64, v67, v70
	v_mov_b32_e32 v70, v56
	v_pk_mul_f32 v[70:71], v[70:71], v[168:169] op_sel_hi:[1,0]
	v_mul_f32_e32 v67, v66, v64
	v_mul_f32_e32 v56, 0xbfb8aa3b, v71
	v_cvt_pk_bf16_f32 v64, v80, v79
	v_cvt_pk_bf16_f32 v65, v76, v74
	v_cvt_pk_bf16_f32 v66, v72, v73
	v_exp_f32_e32 v72, v56
	v_mov_b32_e32 v60, v57
	v_pk_mul_f32 v[56:57], v[60:61], v[168:169] op_sel_hi:[1,0]
	v_cvt_pk_bf16_f32 v67, v68, v67
	v_mad_i64_i32 v[68:69], s[4:5], v154, s51, v[112:113]
	v_mul_f32_e32 v60, 0xbfb8aa3b, v57
	v_exp_f32_e32 v73, v60
	v_lshl_add_u64 v[60:61], v[68:69], 0, v[114:115]
	v_add_f32_e32 v68, 1.0, v72
	v_rcp_f32_e32 v68, v68
	global_store_dwordx4 v[60:61], v[64:67], off
	v_mov_b32_e32 v61, v62
	v_add_f32_e32 v69, 1.0, v73
	v_mul_f32_e32 v60, v71, v68
	v_mul_f32_e32 v64, v70, v60
	v_mov_b32_e32 v60, v58
	v_pk_mul_f32 v[60:61], v[60:61], v[168:169] op_sel_hi:[1,0]
	v_mov_b32_e32 v62, v59
	v_mul_f32_e32 v58, 0xbfb8aa3b, v61
	v_rcp_f32_e32 v69, v69
	v_exp_f32_e32 v65, v58
	v_pk_mul_f32 v[58:59], v[62:63], v[168:169] op_sel_hi:[1,0]
	v_mul_f32_e32 v57, v57, v69
	v_mul_f32_e32 v62, 0xbfb8aa3b, v59
	v_exp_f32_e32 v62, v62
	v_mul_f32_e32 v63, v56, v57
	v_add_f32_e32 v56, 1.0, v65
	v_rcp_f32_e32 v65, v56
	v_add_f32_e32 v56, 1.0, v62
	v_rcp_f32_e32 v62, v56
	v_mov_b32_e32 v56, v48
	v_mov_b32_e32 v57, v52
	v_pk_mul_f32 v[56:57], v[56:57], v[168:169] op_sel_hi:[1,0]
	v_mul_f32_e32 v52, v61, v65
	v_mul_f32_e32 v48, 0xbfb8aa3b, v57
	v_exp_f32_e32 v48, v48
	v_mul_f32_e32 v60, v60, v52
	v_mov_b32_e32 v52, v49
	v_mul_f32_e32 v59, v59, v62
	v_add_f32_e32 v48, 1.0, v48
	v_rcp_f32_e32 v61, v48
	v_pk_mul_f32 v[48:49], v[52:53], v[168:169] op_sel_hi:[1,0]
	v_mul_f32_e32 v58, v58, v59
	v_mul_f32_e32 v52, 0xbfb8aa3b, v49
	v_exp_f32_e32 v52, v52
	v_mul_f32_e32 v53, v57, v61
	v_mul_f32_e32 v56, v56, v53
	v_mov_b32_e32 v53, v54
	v_add_f32_e32 v52, 1.0, v52
	v_rcp_f32_e32 v57, v52
	v_mov_b32_e32 v52, v50
	v_pk_mul_f32 v[52:53], v[52:53], v[168:169] op_sel_hi:[1,0]
	v_mov_b32_e32 v54, v51
	v_mul_f32_e32 v50, 0xbfb8aa3b, v53
	v_exp_f32_e32 v59, v50
	v_pk_mul_f32 v[50:51], v[54:55], v[168:169] op_sel_hi:[1,0]
	v_mul_f32_e32 v49, v49, v57
	v_mul_f32_e32 v54, 0xbfb8aa3b, v51
	v_exp_f32_e32 v54, v54
	v_add_f32_e32 v55, 1.0, v59
	v_rcp_f32_e32 v55, v55
	v_mul_f32_e32 v57, v48, v49
	v_add_f32_e32 v54, 1.0, v54
	v_rcp_f32_e32 v54, v54
	v_mul_f32_e32 v48, v53, v55
	v_mul_f32_e32 v52, v52, v48
	v_mov_b32_e32 v55, v44
	v_mul_f32_e32 v48, v51, v54
	v_mov_b32_e32 v54, v40
	v_pk_mul_f32 v[54:55], v[54:55], v[166:167] op_sel_hi:[1,0]
	v_mul_f32_e32 v51, v50, v48
	v_mul_f32_e32 v40, 0xbfb8aa3b, v55
	v_cvt_pk_bf16_f32 v48, v64, v63
	v_cvt_pk_bf16_f32 v49, v60, v58
	v_cvt_pk_bf16_f32 v50, v56, v57
	v_exp_f32_e32 v56, v40
	v_mov_b32_e32 v44, v41
	v_pk_mul_f32 v[40:41], v[44:45], v[166:167] op_sel_hi:[1,0]
	v_cvt_pk_bf16_f32 v51, v52, v51
	v_mad_i64_i32 v[52:53], s[4:5], v148, s51, v[112:113]
	v_mul_f32_e32 v44, 0xbfb8aa3b, v41
	v_exp_f32_e32 v57, v44
	v_lshl_add_u64 v[44:45], v[52:53], 0, v[114:115]
	v_add_f32_e32 v52, 1.0, v56
	v_rcp_f32_e32 v52, v52
	global_store_dwordx4 v[44:45], v[48:51], off
	v_mov_b32_e32 v45, v46
	v_add_f32_e32 v53, 1.0, v57
	v_mul_f32_e32 v44, v55, v52
	v_mul_f32_e32 v48, v54, v44
	v_mov_b32_e32 v44, v42
	v_pk_mul_f32 v[44:45], v[44:45], v[166:167] op_sel_hi:[1,0]
	v_mov_b32_e32 v46, v43
	v_mul_f32_e32 v42, 0xbfb8aa3b, v45
	v_rcp_f32_e32 v53, v53
	v_exp_f32_e32 v49, v42
	v_pk_mul_f32 v[42:43], v[46:47], v[166:167] op_sel_hi:[1,0]
	v_mul_f32_e32 v41, v41, v53
	v_mul_f32_e32 v46, 0xbfb8aa3b, v43
	v_exp_f32_e32 v46, v46
	v_mul_f32_e32 v47, v40, v41
	v_add_f32_e32 v40, 1.0, v49
	v_rcp_f32_e32 v49, v40
	v_add_f32_e32 v40, 1.0, v46
	v_rcp_f32_e32 v46, v40
	v_mov_b32_e32 v40, v32
	v_mov_b32_e32 v41, v36
	v_pk_mul_f32 v[40:41], v[40:41], v[166:167] op_sel_hi:[1,0]
	v_mul_f32_e32 v36, v45, v49
	v_mul_f32_e32 v32, 0xbfb8aa3b, v41
	v_exp_f32_e32 v32, v32
	v_mul_f32_e32 v44, v44, v36
	v_mov_b32_e32 v36, v33
	v_mul_f32_e32 v43, v43, v46
	v_add_f32_e32 v32, 1.0, v32
	v_rcp_f32_e32 v45, v32
	v_pk_mul_f32 v[32:33], v[36:37], v[166:167] op_sel_hi:[1,0]
	v_mul_f32_e32 v42, v42, v43
	v_mul_f32_e32 v36, 0xbfb8aa3b, v33
	v_exp_f32_e32 v36, v36
	v_mul_f32_e32 v37, v41, v45
	v_mul_f32_e32 v40, v40, v37
	v_mov_b32_e32 v37, v38
	v_add_f32_e32 v36, 1.0, v36
	v_rcp_f32_e32 v41, v36
	v_mov_b32_e32 v36, v34
	v_pk_mul_f32 v[36:37], v[36:37], v[166:167] op_sel_hi:[1,0]
	v_mov_b32_e32 v38, v35
	v_mul_f32_e32 v34, 0xbfb8aa3b, v37
	v_exp_f32_e32 v43, v34
	v_pk_mul_f32 v[34:35], v[38:39], v[166:167] op_sel_hi:[1,0]
	v_mul_f32_e32 v33, v33, v41
	v_mul_f32_e32 v38, 0xbfb8aa3b, v35
	v_exp_f32_e32 v38, v38
	v_add_f32_e32 v39, 1.0, v43
	v_rcp_f32_e32 v39, v39
	v_mul_f32_e32 v41, v32, v33
	v_add_f32_e32 v38, 1.0, v38
	v_rcp_f32_e32 v38, v38
	v_mul_f32_e32 v32, v37, v39
	v_mul_f32_e32 v36, v36, v32
	v_mov_b32_e32 v39, v28
	v_mul_f32_e32 v32, v35, v38
	v_mov_b32_e32 v38, v24
	v_pk_mul_f32 v[38:39], v[38:39], v[164:165] op_sel_hi:[1,0]
	v_mul_f32_e32 v35, v34, v32
	v_mul_f32_e32 v24, 0xbfb8aa3b, v39
	v_cvt_pk_bf16_f32 v32, v48, v47
	v_cvt_pk_bf16_f32 v33, v44, v42
	v_cvt_pk_bf16_f32 v34, v40, v41
	v_exp_f32_e32 v40, v24
	v_mov_b32_e32 v28, v25
	v_pk_mul_f32 v[24:25], v[28:29], v[164:165] op_sel_hi:[1,0]
	v_cvt_pk_bf16_f32 v35, v36, v35
	v_mad_i64_i32 v[36:37], s[4:5], v152, s51, v[112:113]
	v_mul_f32_e32 v28, 0xbfb8aa3b, v25
	v_exp_f32_e32 v41, v28
	v_lshl_add_u64 v[28:29], v[36:37], 0, v[114:115]
	v_add_f32_e32 v36, 1.0, v40
	v_rcp_f32_e32 v36, v36
	global_store_dwordx4 v[28:29], v[32:35], off
	v_mov_b32_e32 v29, v30
	v_add_f32_e32 v37, 1.0, v41
	v_mul_f32_e32 v28, v39, v36
	v_mul_f32_e32 v32, v38, v28
	v_mov_b32_e32 v28, v26
	v_pk_mul_f32 v[28:29], v[28:29], v[164:165] op_sel_hi:[1,0]
	v_mov_b32_e32 v30, v27
	v_mul_f32_e32 v26, 0xbfb8aa3b, v29
	v_rcp_f32_e32 v37, v37
	v_exp_f32_e32 v33, v26
	v_pk_mul_f32 v[26:27], v[30:31], v[164:165] op_sel_hi:[1,0]
	v_mul_f32_e32 v25, v25, v37
	v_mul_f32_e32 v30, 0xbfb8aa3b, v27
	v_exp_f32_e32 v30, v30
	v_mul_f32_e32 v31, v24, v25
	v_add_f32_e32 v24, 1.0, v33
	v_rcp_f32_e32 v33, v24
	v_add_f32_e32 v24, 1.0, v30
	v_rcp_f32_e32 v30, v24
	v_mov_b32_e32 v24, v16
	v_mov_b32_e32 v25, v20
	v_pk_mul_f32 v[24:25], v[24:25], v[164:165] op_sel_hi:[1,0]
	v_mul_f32_e32 v20, v29, v33
	v_mul_f32_e32 v16, 0xbfb8aa3b, v25
	v_exp_f32_e32 v16, v16
	v_mul_f32_e32 v28, v28, v20
	v_mov_b32_e32 v20, v17
	v_mul_f32_e32 v27, v27, v30
	v_add_f32_e32 v16, 1.0, v16
	v_rcp_f32_e32 v29, v16
	v_pk_mul_f32 v[16:17], v[20:21], v[164:165] op_sel_hi:[1,0]
	v_mul_f32_e32 v26, v26, v27
	v_mul_f32_e32 v20, 0xbfb8aa3b, v17
	v_exp_f32_e32 v20, v20
	v_mul_f32_e32 v21, v25, v29
	v_mul_f32_e32 v24, v24, v21
	v_mov_b32_e32 v21, v22
	v_add_f32_e32 v20, 1.0, v20
	v_rcp_f32_e32 v25, v20
	v_mov_b32_e32 v20, v18
	v_pk_mul_f32 v[20:21], v[20:21], v[164:165] op_sel_hi:[1,0]
	v_mov_b32_e32 v22, v19
	v_mul_f32_e32 v18, 0xbfb8aa3b, v21
	v_exp_f32_e32 v27, v18
	v_pk_mul_f32 v[18:19], v[22:23], v[164:165] op_sel_hi:[1,0]
	v_mul_f32_e32 v17, v17, v25
	v_mul_f32_e32 v22, 0xbfb8aa3b, v19
	v_exp_f32_e32 v22, v22
	v_add_f32_e32 v23, 1.0, v27
	v_rcp_f32_e32 v23, v23
	v_mul_f32_e32 v25, v16, v17
	v_add_f32_e32 v22, 1.0, v22
	v_rcp_f32_e32 v22, v22
	v_mul_f32_e32 v16, v21, v23
	v_mul_f32_e32 v20, v20, v16
	v_mov_b32_e32 v23, v12
	v_mul_f32_e32 v16, v19, v22
	v_mov_b32_e32 v22, v8
	v_pk_mul_f32 v[22:23], v[22:23], v[158:159] op_sel_hi:[1,0]
	v_mul_f32_e32 v19, v18, v16
	v_mul_f32_e32 v8, 0xbfb8aa3b, v23
	v_cvt_pk_bf16_f32 v16, v32, v31
	v_cvt_pk_bf16_f32 v17, v28, v26
	v_cvt_pk_bf16_f32 v18, v24, v25
	v_exp_f32_e32 v24, v8
	v_mov_b32_e32 v12, v9
	v_pk_mul_f32 v[8:9], v[12:13], v[158:159] op_sel_hi:[1,0]
	v_cvt_pk_bf16_f32 v19, v20, v19
	v_mad_i64_i32 v[20:21], s[4:5], v150, s51, v[112:113]
	v_mul_f32_e32 v12, 0xbfb8aa3b, v9
	v_exp_f32_e32 v25, v12
	v_lshl_add_u64 v[12:13], v[20:21], 0, v[114:115]
	v_add_f32_e32 v20, 1.0, v24
	v_rcp_f32_e32 v20, v20
	global_store_dwordx4 v[12:13], v[16:19], off
	v_mov_b32_e32 v13, v14
	v_add_f32_e32 v21, 1.0, v25
	v_mul_f32_e32 v12, v23, v20
	v_mul_f32_e32 v16, v22, v12
	v_mov_b32_e32 v12, v10
	v_pk_mul_f32 v[12:13], v[12:13], v[158:159] op_sel_hi:[1,0]
	v_mov_b32_e32 v14, v11
	v_mul_f32_e32 v10, 0xbfb8aa3b, v13
	v_rcp_f32_e32 v21, v21
	v_exp_f32_e32 v17, v10
	v_pk_mul_f32 v[10:11], v[14:15], v[158:159] op_sel_hi:[1,0]
	v_mul_f32_e32 v9, v9, v21
	v_mul_f32_e32 v14, 0xbfb8aa3b, v11
	v_exp_f32_e32 v14, v14
	v_mul_f32_e32 v15, v8, v9
	v_add_f32_e32 v8, 1.0, v17
	v_rcp_f32_e32 v17, v8
	v_add_f32_e32 v8, 1.0, v14
	v_rcp_f32_e32 v14, v8
	v_mov_b32_e32 v8, v0
	v_mov_b32_e32 v9, v4
	v_pk_mul_f32 v[8:9], v[8:9], v[158:159] op_sel_hi:[1,0]
	v_mul_f32_e32 v4, v13, v17
	v_mul_f32_e32 v0, 0xbfb8aa3b, v9
	v_exp_f32_e32 v0, v0
	v_mul_f32_e32 v12, v12, v4
	v_mov_b32_e32 v4, v1
	v_mul_f32_e32 v11, v11, v14
	v_add_f32_e32 v0, 1.0, v0
	v_rcp_f32_e32 v13, v0
	v_pk_mul_f32 v[0:1], v[4:5], v[158:159] op_sel_hi:[1,0]
	v_mul_f32_e32 v10, v10, v11
	v_mul_f32_e32 v4, 0xbfb8aa3b, v1
	v_exp_f32_e32 v4, v4
	v_mul_f32_e32 v5, v9, v13
	v_mul_f32_e32 v8, v8, v5
	v_mov_b32_e32 v5, v6
	v_add_f32_e32 v4, 1.0, v4
	v_rcp_f32_e32 v9, v4
	v_mov_b32_e32 v4, v2
	v_pk_mul_f32 v[4:5], v[4:5], v[158:159] op_sel_hi:[1,0]
	v_mov_b32_e32 v6, v3
	v_mul_f32_e32 v2, 0xbfb8aa3b, v5
	v_exp_f32_e32 v11, v2
	v_pk_mul_f32 v[2:3], v[6:7], v[158:159] op_sel_hi:[1,0]
	v_mul_f32_e32 v1, v1, v9
	v_mul_f32_e32 v6, 0xbfb8aa3b, v3
	v_exp_f32_e32 v6, v6
	v_add_f32_e32 v7, 1.0, v11
	v_rcp_f32_e32 v7, v7
	v_mul_f32_e32 v9, v0, v1
	v_add_f32_e32 v6, 1.0, v6
	v_rcp_f32_e32 v6, v6
	v_mul_f32_e32 v0, v5, v7
	v_mul_f32_e32 v4, v4, v0
	v_mul_f32_e32 v0, v3, v6
	v_mul_f32_e32 v3, v2, v0
	v_cvt_pk_bf16_f32 v0, v16, v15
	v_cvt_pk_bf16_f32 v1, v12, v10
	v_cvt_pk_bf16_f32 v2, v8, v9
	v_cvt_pk_bf16_f32 v3, v4, v3
	v_mad_i64_i32 v[4:5], s[4:5], v146, s51, v[112:113]
	v_lshl_add_u64 v[4:5], v[4:5], 0, v[114:115]
	s_mov_b64 s[4:5], -1
	global_store_dwordx4 v[4:5], v[0:3], off
	s_cbranch_vccnz .LBB0_1044
	s_andn2_b64 vcc, exec, s[16:17]
	s_cbranch_vccnz .LBB0_1043
	s_mov_b32 s90, 1
	s_branch .LBB0_1043
